# t8 + grid barrier: non-leader workgroups poll the top generation word directly (one hop fewer)
# speedup vs baseline: 1.0065x; 1.0030x over previous
.LBB0_380:
	s_lshl_b32 s22, s40, 6
	s_add_i32 s4, s22, 0x500
	s_mov_b32 s5, 0
	s_lshl_b64 s[0:1], s[4:5], 2
	s_add_u32 s0, s38, s0
	s_addc_u32 s1, s39, s1
	v_mov_b32_e32 v1, 1
	v_mov_b64_e32 v[4:5], s[0:1]
	flat_atomic_add v1, v[4:5], v1 sc0
	v_cvt_f32_u32_e32 v3, v2
	v_sub_u32_e32 v4, 0, v2
	v_rcp_iflag_f32_e32 v3, v3
	s_nop 0
	v_mul_f32_e32 v3, 0x4f7ffffe, v3
	v_cvt_u32_f32_e32 v3, v3
	v_mul_lo_u32 v4, v4, v3
	v_mul_hi_u32 v4, v3, v4
	v_add_u32_e32 v3, v3, v4
	s_waitcnt vmcnt(0) lgkmcnt(0)
	v_mul_hi_u32 v3, v1, v3
	v_mul_lo_u32 v5, v3, v2
	v_add_u32_e32 v4, 1, v1
	v_sub_u32_e32 v1, v1, v5
	v_add_u32_e32 v6, 1, v3
	v_cmp_ge_u32_e32 vcc, v1, v2
	v_sub_u32_e32 v5, v1, v2
	s_nop 0
	v_cndmask_b32_e32 v3, v3, v6, vcc
	v_cndmask_b32_e32 v1, v1, v5, vcc
	v_add_u32_e32 v5, 1, v3
	v_cmp_ge_u32_e32 vcc, v1, v2
	s_nop 1
	v_cndmask_b32_e32 v1, v3, v5, vcc
	v_mad_u64_u32 v[2:3], s[0:1], v2, v1, v[2:3]
	v_cmp_ne_u32_e32 vcc, v4, v2
	s_and_saveexec_b64 s[0:1], vcc
	s_xor_b64 s[0:1], exec, s[0:1]
	s_cbranch_execz .LBB0_393
	s_movk_i32 s4, 0xd40
	s_lshl_b64 s[4:5], s[4:5], 2
	s_add_u32 s6, s38, s4
	s_addc_u32 s7, s39, s5
	v_mov_b64_e32 v[2:3], s[6:7]
	flat_load_dword v0, v[2:3] sc1
	s_waitcnt vmcnt(0) lgkmcnt(0)
	v_cmp_eq_u32_e32 vcc, v0, v1
	s_and_saveexec_b64 s[4:5], vcc
	s_cbranch_execz .LBB0_392
	s_mov_b32 s23, 1
	s_mov_b64 s[8:9], 0
	s_branch .LBB0_384

.LBB0_477:
	s_lshl_b32 s24, s40, 6
	s_add_i32 s48, s24, 0x500
	s_lshl_b64 s[4:5], s[48:49], 2
	s_add_u32 s4, s38, s4
	s_addc_u32 s5, s39, s5
	v_mov_b64_e32 v[4:5], s[4:5]
	v_mov_b32_e32 v3, 1
	flat_atomic_add v4, v[4:5], v3 sc0
	v_cvt_f32_u32_e32 v3, v2
	v_sub_u32_e32 v5, 0, v2
	v_rcp_iflag_f32_e32 v3, v3
	s_nop 0
	v_mul_f32_e32 v3, 0x4f7ffffe, v3
	v_cvt_u32_f32_e32 v3, v3
	v_mul_lo_u32 v5, v5, v3
	v_mul_hi_u32 v5, v3, v5
	v_add_u32_e32 v3, v3, v5
	s_waitcnt vmcnt(0) lgkmcnt(0)
	v_mul_hi_u32 v3, v4, v3
	v_mul_lo_u32 v5, v3, v2
	v_sub_u32_e32 v5, v4, v5
	v_cmp_ge_u32_e32 vcc, v5, v2
	v_add_u32_e32 v6, 1, v3
	s_nop 0
	v_cndmask_b32_e32 v3, v3, v6, vcc
	v_sub_u32_e32 v6, v5, v2
	v_cndmask_b32_e32 v5, v5, v6, vcc
	v_cmp_ge_u32_e32 vcc, v5, v2
	v_add_u32_e32 v5, 1, v3
	v_add_u32_e32 v6, 1, v4
	v_cndmask_b32_e32 v3, v3, v5, vcc
	v_mad_u64_u32 v[4:5], s[4:5], v2, v3, v[2:3]
	v_cmp_ne_u32_e32 vcc, v6, v4
	s_and_saveexec_b64 s[4:5], vcc
	s_xor_b64 s[4:5], exec, s[4:5]
	s_cbranch_execz .LBB0_490
	s_movk_i32 s48, 0xd40
	s_lshl_b64 s[6:7], s[48:49], 2
	s_add_u32 s8, s38, s6
	s_addc_u32 s9, s39, s7
	v_mov_b64_e32 v[4:5], s[8:9]
	flat_load_dword v0, v[4:5] sc1
	s_waitcnt vmcnt(0) lgkmcnt(0)
	v_cmp_eq_u32_e32 vcc, v0, v3
	s_and_saveexec_b64 s[6:7], vcc
	s_cbranch_execz .LBB0_489
	s_mov_b32 s25, 1
	s_mov_b64 s[10:11], 0
	s_branch .LBB0_481

.LBB0_603:
	s_lshl_b32 s28, s40, 6
	s_add_i32 s48, s28, 0x500
	s_lshl_b64 s[8:9], s[48:49], 2
	s_add_u32 s8, s6, s8
	s_addc_u32 s9, s7, s9
	v_mov_b64_e32 v[4:5], s[8:9]
	v_mov_b32_e32 v3, 1
	flat_atomic_add v4, v[4:5], v3 sc0
	v_cvt_f32_u32_e32 v3, v2
	v_sub_u32_e32 v5, 0, v2
	v_rcp_iflag_f32_e32 v3, v3
	s_nop 0
	v_mul_f32_e32 v3, 0x4f7ffffe, v3
	v_cvt_u32_f32_e32 v3, v3
	v_mul_lo_u32 v5, v5, v3
	v_mul_hi_u32 v5, v3, v5
	v_add_u32_e32 v3, v3, v5
	s_waitcnt vmcnt(0) lgkmcnt(0)
	v_mul_hi_u32 v3, v4, v3
	v_mul_lo_u32 v5, v3, v2
	v_sub_u32_e32 v5, v4, v5
	v_cmp_ge_u32_e32 vcc, v5, v2
	v_add_u32_e32 v6, 1, v3
	s_nop 0
	v_cndmask_b32_e32 v3, v3, v6, vcc
	v_sub_u32_e32 v6, v5, v2
	v_cndmask_b32_e32 v5, v5, v6, vcc
	v_cmp_ge_u32_e32 vcc, v5, v2
	v_add_u32_e32 v5, 1, v3
	v_add_u32_e32 v6, 1, v4
	v_cndmask_b32_e32 v3, v3, v5, vcc
	v_mad_u64_u32 v[4:5], s[8:9], v2, v3, v[2:3]
	v_cmp_ne_u32_e32 vcc, v6, v4
	s_and_saveexec_b64 s[8:9], vcc
	s_xor_b64 s[8:9], exec, s[8:9]
	s_cbranch_execz .LBB0_616
	s_movk_i32 s48, 0xd40
	s_lshl_b64 s[10:11], s[48:49], 2
	s_add_u32 s12, s6, s10
	s_addc_u32 s13, s7, s11
	v_mov_b64_e32 v[4:5], s[12:13]
	flat_load_dword v0, v[4:5] sc1
	s_waitcnt vmcnt(0) lgkmcnt(0)
	v_cmp_eq_u32_e32 vcc, v0, v3
	s_and_saveexec_b64 s[10:11], vcc
	s_cbranch_execz .LBB0_615
	s_mov_b32 s29, 1
	s_mov_b64 s[14:15], 0
	s_branch .LBB0_607

.LBB0_778:
	s_lshl_b32 s28, s48, 6
	s_add_i32 s48, s28, 0x500
	s_lshl_b64 s[8:9], s[48:49], 2
	s_add_u32 s8, s6, s8
	s_addc_u32 s9, s7, s9
	v_mov_b64_e32 v[4:5], s[8:9]
	v_mov_b32_e32 v3, 1
	flat_atomic_add v4, v[4:5], v3 sc0
	v_cvt_f32_u32_e32 v3, v2
	v_sub_u32_e32 v5, 0, v2
	v_rcp_iflag_f32_e32 v3, v3
	s_nop 0
	v_mul_f32_e32 v3, 0x4f7ffffe, v3
	v_cvt_u32_f32_e32 v3, v3
	v_mul_lo_u32 v5, v5, v3
	v_mul_hi_u32 v5, v3, v5
	v_add_u32_e32 v3, v3, v5
	s_waitcnt vmcnt(0) lgkmcnt(0)
	v_mul_hi_u32 v3, v4, v3
	v_mul_lo_u32 v5, v3, v2
	v_sub_u32_e32 v5, v4, v5
	v_cmp_ge_u32_e32 vcc, v5, v2
	v_add_u32_e32 v6, 1, v3
	s_nop 0
	v_cndmask_b32_e32 v3, v3, v6, vcc
	v_sub_u32_e32 v6, v5, v2
	v_cndmask_b32_e32 v5, v5, v6, vcc
	v_cmp_ge_u32_e32 vcc, v5, v2
	v_add_u32_e32 v5, 1, v3
	v_add_u32_e32 v6, 1, v4
	v_cndmask_b32_e32 v3, v3, v5, vcc
	v_mad_u64_u32 v[4:5], s[8:9], v2, v3, v[2:3]
	v_cmp_ne_u32_e32 vcc, v6, v4
	s_and_saveexec_b64 s[8:9], vcc
	s_xor_b64 s[8:9], exec, s[8:9]
	s_cbranch_execz .LBB0_791
	s_movk_i32 s48, 0xd40
	s_lshl_b64 s[10:11], s[48:49], 2
	s_add_u32 s12, s6, s10
	s_addc_u32 s13, s7, s11
	v_mov_b64_e32 v[4:5], s[12:13]
	flat_load_dword v0, v[4:5] sc1
	s_waitcnt vmcnt(0) lgkmcnt(0)
	v_cmp_eq_u32_e32 vcc, v0, v3
	s_and_saveexec_b64 s[10:11], vcc
	s_cbranch_execz .LBB0_790
	s_mov_b32 s29, 1
	s_mov_b64 s[14:15], 0
	s_branch .LBB0_782

.LBB0_852:
	s_lshl_b32 s28, s42, 6
	s_add_i32 s48, s28, 0x500
	s_lshl_b64 s[8:9], s[48:49], 2
	s_add_u32 s8, s6, s8
	s_addc_u32 s9, s7, s9
	v_mov_b64_e32 v[4:5], s[8:9]
	v_mov_b32_e32 v3, 1
	flat_atomic_add v4, v[4:5], v3 sc0
	v_cvt_f32_u32_e32 v3, v2
	v_sub_u32_e32 v5, 0, v2
	v_rcp_iflag_f32_e32 v3, v3
	s_nop 0
	v_mul_f32_e32 v3, 0x4f7ffffe, v3
	v_cvt_u32_f32_e32 v3, v3
	v_mul_lo_u32 v5, v5, v3
	v_mul_hi_u32 v5, v3, v5
	v_add_u32_e32 v3, v3, v5
	s_waitcnt vmcnt(0) lgkmcnt(0)
	v_mul_hi_u32 v3, v4, v3
	v_mul_lo_u32 v5, v3, v2
	v_sub_u32_e32 v5, v4, v5
	v_cmp_ge_u32_e32 vcc, v5, v2
	v_add_u32_e32 v6, 1, v3
	s_nop 0
	v_cndmask_b32_e32 v3, v3, v6, vcc
	v_sub_u32_e32 v6, v5, v2
	v_cndmask_b32_e32 v5, v5, v6, vcc
	v_cmp_ge_u32_e32 vcc, v5, v2
	v_add_u32_e32 v5, 1, v3
	v_add_u32_e32 v6, 1, v4
	v_cndmask_b32_e32 v3, v3, v5, vcc
	v_mad_u64_u32 v[4:5], s[8:9], v2, v3, v[2:3]
	v_cmp_ne_u32_e32 vcc, v6, v4
	s_and_saveexec_b64 s[8:9], vcc
	s_xor_b64 s[8:9], exec, s[8:9]
	s_cbranch_execz .LBB0_865
	s_movk_i32 s48, 0xd40
	s_lshl_b64 s[10:11], s[48:49], 2
	s_add_u32 s12, s6, s10
	s_addc_u32 s13, s7, s11
	v_mov_b64_e32 v[4:5], s[12:13]
	flat_load_dword v0, v[4:5] sc1
	s_waitcnt vmcnt(0) lgkmcnt(0)
	v_cmp_eq_u32_e32 vcc, v0, v3
	s_and_saveexec_b64 s[10:11], vcc
	s_cbranch_execz .LBB0_864
	s_mov_b32 s29, 1
	s_mov_b64 s[14:15], 0
	s_branch .LBB0_856

.LBB0_1331:
	s_lshl_b32 s30, s48, 6
	s_add_i32 s48, s30, 0x500
	s_lshl_b64 s[10:11], s[48:49], 2
	s_add_u32 s10, s6, s10
	s_addc_u32 s11, s7, s11
	v_mov_b64_e32 v[4:5], s[10:11]
	v_mov_b32_e32 v3, 1
	flat_atomic_add v4, v[4:5], v3 sc0
	v_cvt_f32_u32_e32 v3, v2
	v_sub_u32_e32 v5, 0, v2
	v_rcp_iflag_f32_e32 v3, v3
	s_nop 0
	v_mul_f32_e32 v3, 0x4f7ffffe, v3
	v_cvt_u32_f32_e32 v3, v3
	v_mul_lo_u32 v5, v5, v3
	v_mul_hi_u32 v5, v3, v5
	v_add_u32_e32 v3, v3, v5
	s_waitcnt vmcnt(0) lgkmcnt(0)
	v_mul_hi_u32 v3, v4, v3
	v_mul_lo_u32 v5, v3, v2
	v_sub_u32_e32 v5, v4, v5
	v_cmp_ge_u32_e32 vcc, v5, v2
	v_add_u32_e32 v6, 1, v3
	s_nop 0
	v_cndmask_b32_e32 v3, v3, v6, vcc
	v_sub_u32_e32 v6, v5, v2
	v_cndmask_b32_e32 v5, v5, v6, vcc
	v_cmp_ge_u32_e32 vcc, v5, v2
	v_add_u32_e32 v5, 1, v3
	v_add_u32_e32 v6, 1, v4
	v_cndmask_b32_e32 v3, v3, v5, vcc
	v_mad_u64_u32 v[4:5], s[10:11], v2, v3, v[2:3]
	v_cmp_ne_u32_e32 vcc, v6, v4
	s_and_saveexec_b64 s[10:11], vcc
	s_xor_b64 s[10:11], exec, s[10:11]
	s_cbranch_execz .LBB0_1344
	s_movk_i32 s48, 0xd40
	s_lshl_b64 s[12:13], s[48:49], 2
	s_add_u32 s14, s6, s12
	s_addc_u32 s15, s7, s13
	v_mov_b64_e32 v[4:5], s[14:15]
	flat_load_dword v0, v[4:5] sc1
	s_waitcnt vmcnt(0) lgkmcnt(0)
	v_cmp_eq_u32_e32 vcc, v0, v3
	s_and_saveexec_b64 s[12:13], vcc
	s_cbranch_execz .LBB0_1343
	s_mov_b32 s31, 1
	s_mov_b64 s[16:17], 0
	s_branch .LBB0_1335

.LBB0_1742:
	s_lshl_b32 s26, s41, 6
	s_add_i32 s48, s26, 0x500
	s_lshl_b64 s[4:5], s[48:49], 2
	s_add_u32 s4, s38, s4
	s_addc_u32 s5, s39, s5
	v_mov_b64_e32 v[4:5], s[4:5]
	v_mov_b32_e32 v3, 1
	flat_atomic_add v4, v[4:5], v3 sc0
	v_cvt_f32_u32_e32 v3, v2
	v_sub_u32_e32 v5, 0, v2
	v_rcp_iflag_f32_e32 v3, v3
	s_nop 0
	v_mul_f32_e32 v3, 0x4f7ffffe, v3
	v_cvt_u32_f32_e32 v3, v3
	v_mul_lo_u32 v5, v5, v3
	v_mul_hi_u32 v5, v3, v5
	v_add_u32_e32 v3, v3, v5
	s_waitcnt vmcnt(0) lgkmcnt(0)
	v_mul_hi_u32 v3, v4, v3
	v_mul_lo_u32 v5, v3, v2
	v_sub_u32_e32 v5, v4, v5
	v_cmp_ge_u32_e32 vcc, v5, v2
	v_add_u32_e32 v6, 1, v3
	s_nop 0
	v_cndmask_b32_e32 v3, v3, v6, vcc
	v_sub_u32_e32 v6, v5, v2
	v_cndmask_b32_e32 v5, v5, v6, vcc
	v_cmp_ge_u32_e32 vcc, v5, v2
	v_add_u32_e32 v5, 1, v3
	v_add_u32_e32 v6, 1, v4
	v_cndmask_b32_e32 v3, v3, v5, vcc
	v_mad_u64_u32 v[4:5], s[4:5], v2, v3, v[2:3]
	v_cmp_ne_u32_e32 vcc, v6, v4
	s_and_saveexec_b64 s[4:5], vcc
	s_xor_b64 s[4:5], exec, s[4:5]
	s_cbranch_execz .LBB0_1755
	s_movk_i32 s48, 0xd40
	s_lshl_b64 s[6:7], s[48:49], 2
	s_add_u32 s8, s38, s6
	s_addc_u32 s9, s39, s7
	v_mov_b64_e32 v[4:5], s[8:9]
	flat_load_dword v0, v[4:5] sc1
	s_waitcnt vmcnt(0) lgkmcnt(0)
	v_cmp_eq_u32_e32 vcc, v0, v3
	s_and_saveexec_b64 s[6:7], vcc
	s_cbranch_execz .LBB0_1754
	s_mov_b32 s27, 1
	s_mov_b64 s[10:11], 0
	s_branch .LBB0_1746
